# LDS double-buffered main loops (writes interleaved with MFMAs, one barrier per k-step, 2-deep register prefetch) for gemm_in and gemm_out
# speedup vs baseline: 1.1863x; 1.0063x over previous
.LBB0_329:
	v_mov_b32_e32 v10, v231
	ds_read_b64 v[134:135], v229 offset:63760
	ds_read_b64 v[136:137], v229 offset:63760
	s_ashr_i32 s7, s6, 31
	s_lshl_b64 s[2:3], s[6:7], 18
	v_ashrrev_i32_e32 v4, 3, v10
	v_ashrrev_i32_e32 v5, 31, v4
	v_lshl_add_u64 v[0:1], v[132:133], 0, s[2:3]
	v_lshlrev_b64 v[6:7], 11, v[4:5]
	v_lshlrev_b32_e32 v5, 4, v10
	s_ashr_i32 s1, s0, 31
	v_lshl_add_u64 v[0:1], v[0:1], 0, v[6:7]
	v_and_b32_e32 v228, 0x70, v5
	s_lshl_b64 s[4:5], s[0:1], 18
	v_lshl_add_u64 v[0:1], v[0:1], 0, v[228:229]
	s_mov_b32 s1, 0x10000
	v_add_co_u32_e32 v8, vcc, s1, v0
	v_lshl_add_u64 v[2:3], v[130:131], 0, s[4:5]
	s_nop 0
	v_addc_co_u32_e32 v9, vcc, 0, v1, vcc
	s_mov_b32 s4, 0x20000
	global_load_dwordx4 v[64:67], v[0:1], off
	global_load_dwordx4 v[68:71], v[8:9], off
	v_add_co_u32_e32 v8, vcc, s4, v0
	s_mov_b32 s5, 0x30000
	s_nop 0
	v_addc_co_u32_e32 v9, vcc, 0, v1, vcc
	v_lshl_add_u64 v[2:3], v[2:3], 0, v[6:7]
	v_add_co_u32_e32 v0, vcc, s5, v0
	v_lshl_add_u64 v[138:139], v[2:3], 0, v[228:229]
	s_nop 0
	v_addc_co_u32_e32 v1, vcc, 0, v1, vcc
	global_load_dwordx4 v[72:75], v[8:9], off
	global_load_dwordx4 v[76:79], v[0:1], off
	v_add_co_u32_e32 v0, vcc, s1, v138
	global_load_dwordx4 v[80:83], v[138:139], off
	s_nop 0
	v_addc_co_u32_e32 v1, vcc, 0, v139, vcc
	v_add_co_u32_e32 v2, vcc, s4, v138
	s_movk_i32 s1, 0x90
	s_nop 0
	v_addc_co_u32_e32 v3, vcc, 0, v139, vcc
	global_load_dwordx4 v[84:87], v[0:1], off
	global_load_dwordx4 v[88:91], v[2:3], off
	v_add_co_u32_e32 v0, vcc, s5, v138
	v_mad_u64_u32 v[140:141], s[4:5], v4, s1, v[228:229]
	s_nop 0
	v_addc_co_u32_e32 v1, vcc, 0, v139, vcc
	global_load_dwordx4 v[92:95], v[0:1], off
	v_ashrrev_i32_e32 v0, 1, v10
	v_bfe_u32 v141, v10, 5, 1
	v_and_b32_e32 v146, 0xffffffc0, v0
	v_and_or_b32 v1, v10, 31, v146
	v_lshlrev_b32_e32 v0, 4, v141
	v_mad_u64_u32 v[142:143], s[4:5], v1, s1, v[0:1]
	v_and_b32_e32 v143, 0x5f, v10
	v_mad_u32_u24 v147, v143, s1, v0
	v_lshl_add_u64 v[0:1], s[2:3], 0, v[6:7]
	v_and_b32_e32 v2, 7, v10
	v_lshl_or_b32 v0, v2, 4, v0
	v_lshl_add_u64 v[144:145], v[128:129], 0, v[0:1]
	v_mov_b32_e32 v0, 0
	s_mov_b64 s[2:3], 0
	v_mov_b32_e32 v1, v0
	v_mov_b32_e32 v2, v0
	v_mov_b32_e32 v3, v0
	v_mov_b32_e32 v4, v0
	v_mov_b32_e32 v5, v0
	v_mov_b32_e32 v6, v0
	v_mov_b32_e32 v7, v0
	v_mov_b32_e32 v8, v0
	v_mov_b32_e32 v9, v0
	v_mov_b32_e32 v10, v0
	v_mov_b32_e32 v11, v0
	v_mov_b32_e32 v12, v0
	v_mov_b32_e32 v13, v0
	v_mov_b32_e32 v14, v0
	v_mov_b32_e32 v15, v0
	v_mov_b32_e32 v16, v0
	v_mov_b32_e32 v17, v0
	v_mov_b32_e32 v18, v0
	v_mov_b32_e32 v19, v0
	v_mov_b32_e32 v20, v0
	v_mov_b32_e32 v21, v0
	v_mov_b32_e32 v22, v0
	v_mov_b32_e32 v23, v0
	v_mov_b32_e32 v24, v0
	v_mov_b32_e32 v25, v0
	v_mov_b32_e32 v26, v0
	v_mov_b32_e32 v27, v0
	v_mov_b32_e32 v28, v0
	v_mov_b32_e32 v29, v0
	v_mov_b32_e32 v30, v0
	v_mov_b32_e32 v31, v0
	v_mov_b32_e32 v32, v0
	v_mov_b32_e32 v33, v0
	v_mov_b32_e32 v34, v0
	v_mov_b32_e32 v35, v0
	v_mov_b32_e32 v36, v0
	v_mov_b32_e32 v37, v0
	v_mov_b32_e32 v38, v0
	v_mov_b32_e32 v39, v0
	v_mov_b32_e32 v40, v0
	v_mov_b32_e32 v41, v0
	v_mov_b32_e32 v42, v0
	v_mov_b32_e32 v43, v0
	v_mov_b32_e32 v44, v0
	v_mov_b32_e32 v45, v0
	v_mov_b32_e32 v46, v0
	v_mov_b32_e32 v47, v0
	v_mov_b32_e32 v48, v0
	v_mov_b32_e32 v49, v0
	v_mov_b32_e32 v50, v0
	v_mov_b32_e32 v51, v0
	v_mov_b32_e32 v52, v0
	v_mov_b32_e32 v53, v0
	v_mov_b32_e32 v54, v0
	v_mov_b32_e32 v55, v0
	v_mov_b32_e32 v56, v0
	v_mov_b32_e32 v57, v0
	v_mov_b32_e32 v58, v0
	v_mov_b32_e32 v59, v0
	v_mov_b32_e32 v60, v0
	v_mov_b32_e32 v61, v0
	v_mov_b32_e32 v62, v0
	v_mov_b32_e32 v63, v0
	v_lshrrev_b32_e32 v152, 3, v231
	v_cmp_gt_u32_e32 vcc, 24, v152
	v_mov_b32_e32 v153, 0xebc0
	v_mov_b32_e32 v148, 0xea00
	v_add_u32_e32 v149, 0x10fc0, v140
	v_cndmask_b32_e32 v148, v153, v148, vcc
	v_and_b32_e32 v152, 0x5f, v231
	v_cmp_gt_u32_e32 vcc, 56, v152
	v_mov_b32_e32 v153, 0xd9c0
	v_mov_b32_e32 v150, 0xd800
	v_add_u32_e32 v148, v148, v140
	v_cndmask_b32_e32 v150, v153, v150, vcc
	v_add_u32_e32 v152, 32, v152
	v_cmp_gt_u32_e32 vcc, 56, v152
	v_mov_b32_e32 v151, 0xd800
	v_add_u32_e32 v150, v150, v147
	v_add_u32_e32 v152, 0x1200, v147
	v_cndmask_b32_e32 v151, v153, v151, vcc
	v_add_u32_e32 v151, v151, v152
	v_lshl_add_u64 v[168:169], v[144:145], 0, s[2:3]
	v_add_co_u32_e32 v160, vcc, 0x4ad4000, v168
	v_lshl_add_u64 v[184:185], v[138:139], 0, s[2:3]
	s_nop 0
	v_addc_co_u32_e32 v161, vcc, 0, v169, vcc
	v_add_co_u32_e32 v164, vcc, 0x4ae4000, v168
	s_nop 1
	v_addc_co_u32_e32 v165, vcc, 0, v169, vcc
	v_add_co_u32_e32 v170, vcc, 0x4af4000, v168
	global_load_dwordx4 v[160:163], v[160:161], off offset:128
	s_nop 0
	global_load_dwordx4 v[164:167], v[164:165], off offset:128
	v_addc_co_u32_e32 v171, vcc, 0, v169, vcc
	v_add_co_u32_e32 v172, vcc, 0x4b04000, v168
	s_nop 1
	v_addc_co_u32_e32 v173, vcc, 0, v169, vcc
	v_add_co_u32_e32 v180, vcc, 0x10000, v184
	global_load_dwordx4 v[168:171], v[170:171], off offset:128
	s_nop 0
	global_load_dwordx4 v[172:175], v[172:173], off offset:128
	v_addc_co_u32_e32 v181, vcc, 0, v185, vcc
	v_add_co_u32_e32 v186, vcc, 0x20000, v184
	global_load_dwordx4 v[176:179], v[184:185], off offset:128
	s_nop 0
	global_load_dwordx4 v[180:183], v[180:181], off offset:128
	v_addc_co_u32_e32 v187, vcc, 0, v185, vcc
	v_add_co_u32_e32 v188, vcc, 0x30000, v184
	s_nop 1
	v_addc_co_u32_e32 v189, vcc, 0, v185, vcc
	global_load_dwordx4 v[184:187], v[186:187], off offset:128
	s_nop 0
	global_load_dwordx4 v[188:191], v[188:189], off offset:128
	s_waitcnt vmcnt(8)
	ds_write_b128 v140, v[64:67]
	ds_write_b128 v140, v[68:71] offset:4608
	ds_write_b128 v140, v[72:75] offset:9216
	ds_write_b128 v140, v[76:79] offset:13824
	ds_write_b128 v140, v[80:83] offset:18432
	ds_write_b128 v140, v[84:87] offset:23040
	ds_write_b128 v140, v[88:91] offset:27648
	ds_write_b128 v140, v[92:95] offset:32256
	s_waitcnt lgkmcnt(0)
	s_barrier
.Lgi_even:
	ds_read_b128 v[112:115], v142
	ds_read_b128 v[96:99], v142 offset:32
	ds_read_b128 v[120:123], v147 offset:18432
	ds_read_b128 v[100:103], v147 offset:18464
	ds_read_b128 v[116:119], v142 offset:4608
	ds_read_b128 v[104:107], v142 offset:4640
	ds_read_b128 v[124:127], v147 offset:23040
	ds_read_b128 v[108:111], v147 offset:23072
	s_cmp_ge_u32 s2, 0x700
	s_cbranch_scc1 .Lgi_even_nold
	v_lshl_add_u64 v[72:73], v[144:145], 0, s[2:3]
	v_add_co_u32_e32 v64, vcc, 0x4ad4000, v72
	v_lshl_add_u64 v[88:89], v[138:139], 0, s[2:3]
	s_nop 0
	v_addc_co_u32_e32 v65, vcc, 0, v73, vcc
	v_add_co_u32_e32 v68, vcc, 0x4ae4000, v72
	s_nop 1
	v_addc_co_u32_e32 v69, vcc, 0, v73, vcc
	v_add_co_u32_e32 v74, vcc, 0x4af4000, v72
	global_load_dwordx4 v[64:67], v[64:65], off offset:256
	s_nop 0
	global_load_dwordx4 v[68:71], v[68:69], off offset:256
	v_addc_co_u32_e32 v75, vcc, 0, v73, vcc
	v_add_co_u32_e32 v76, vcc, 0x4b04000, v72
	s_nop 1
	v_addc_co_u32_e32 v77, vcc, 0, v73, vcc
	v_add_co_u32_e32 v84, vcc, 0x10000, v88
	global_load_dwordx4 v[72:75], v[74:75], off offset:256
	s_nop 0
	global_load_dwordx4 v[76:79], v[76:77], off offset:256
	v_addc_co_u32_e32 v85, vcc, 0, v89, vcc
	v_add_co_u32_e32 v90, vcc, 0x20000, v88
	global_load_dwordx4 v[80:83], v[88:89], off offset:256
	s_nop 0
	global_load_dwordx4 v[84:87], v[84:85], off offset:256
	v_addc_co_u32_e32 v91, vcc, 0, v89, vcc
	v_add_co_u32_e32 v92, vcc, 0x30000, v88
	s_nop 1
	v_addc_co_u32_e32 v93, vcc, 0, v89, vcc
	global_load_dwordx4 v[88:91], v[90:91], off offset:256
	s_nop 0
	global_load_dwordx4 v[92:95], v[92:93], off offset:256
.Lgi_even_nold:
	s_cmp_ge_u32 s2, 0x700
	s_cbranch_scc1 .Lgi_even_w0
	s_waitcnt vmcnt(8)
	s_branch .Lgi_even_w1

.Lgi_even_w1:
	s_waitcnt lgkmcnt(5)
	v_mfma_f32_32x32x16_bf16 v[48:63], v[112:115], v[120:123], v[48:63]
	s_waitcnt lgkmcnt(1)
	v_mfma_f32_32x32x16_bf16 v[32:47], v[112:115], v[124:127], v[32:47]
	v_mfma_f32_32x32x16_bf16 v[16:31], v[116:119], v[120:123], v[16:31]
	v_mfma_f32_32x32x16_bf16 v[0:15], v[116:119], v[124:127], v[0:15]
	ds_write_b128 v140, v[160:163] offset:36864
	ds_write_b128 v140, v[164:167] offset:41472
	ds_write_b128 v140, v[168:171] offset:46080
	ds_write_b128 v140, v[172:175] offset:50688
	ds_read_b128 v[112:115], v142 offset:64
	ds_read_b128 v[116:119], v142 offset:4672
	ds_read_b128 v[120:123], v147 offset:18496
	ds_read_b128 v[124:127], v147 offset:23104
	s_waitcnt lgkmcnt(8)
	v_mfma_f32_32x32x16_bf16 v[48:63], v[96:99], v[100:103], v[48:63]
	v_mfma_f32_32x32x16_bf16 v[32:47], v[96:99], v[108:111], v[32:47]
	v_mfma_f32_32x32x16_bf16 v[16:31], v[104:107], v[100:103], v[16:31]
	v_mfma_f32_32x32x16_bf16 v[0:15], v[104:107], v[108:111], v[0:15]
	ds_write_b128 v140, v[176:179] offset:55296
	ds_write_b128 v148, v[180:183]
	ds_write_b128 v140, v[184:187] offset:64960
	ds_write_b128 v149, v[188:191]
	ds_read_b128 v[96:99], v142 offset:96
	ds_read_b128 v[100:103], v142 offset:4704
	ds_read_b128 v[104:107], v147 offset:18528
	ds_read_b128 v[108:111], v147 offset:23136
	s_waitcnt lgkmcnt(9)
	v_mfma_f32_32x32x16_bf16 v[48:63], v[112:115], v[120:123], v[48:63]
	s_waitcnt lgkmcnt(8)
	v_mfma_f32_32x32x16_bf16 v[32:47], v[112:115], v[124:127], v[32:47]
	v_mfma_f32_32x32x16_bf16 v[16:31], v[116:119], v[120:123], v[16:31]
	v_mfma_f32_32x32x16_bf16 v[0:15], v[116:119], v[124:127], v[0:15]
	s_waitcnt lgkmcnt(1)
	v_mfma_f32_32x32x16_bf16 v[48:63], v[96:99], v[104:107], v[48:63]
	s_waitcnt lgkmcnt(0)
	v_mfma_f32_32x32x16_bf16 v[32:47], v[96:99], v[108:111], v[32:47]
	v_mfma_f32_32x32x16_bf16 v[16:31], v[100:103], v[104:107], v[16:31]
	v_mfma_f32_32x32x16_bf16 v[0:15], v[100:103], v[108:111], v[0:15]
	s_waitcnt lgkmcnt(0)
	s_barrier
	s_add_u32 s2, s2, 0x80
	s_addc_u32 s3, s3, 0
.Lgi_odd:
	ds_read_b128 v[112:115], v142 offset:36864
	ds_read_b128 v[96:99], v142 offset:36896
	ds_read_b128 v[120:123], v150
	ds_read_b128 v[100:103], v150 offset:32
	ds_read_b128 v[116:119], v142 offset:41472
	ds_read_b128 v[104:107], v142 offset:41504
	ds_read_b128 v[124:127], v151
	ds_read_b128 v[108:111], v151 offset:32
	s_cmp_ge_u32 s2, 0x700
	s_cbranch_scc1 .Lgi_odd_nold
	v_lshl_add_u64 v[168:169], v[144:145], 0, s[2:3]
	v_add_co_u32_e32 v160, vcc, 0x4ad4000, v168
	v_lshl_add_u64 v[184:185], v[138:139], 0, s[2:3]
	s_nop 0
	v_addc_co_u32_e32 v161, vcc, 0, v169, vcc
	v_add_co_u32_e32 v164, vcc, 0x4ae4000, v168
	s_nop 1
	v_addc_co_u32_e32 v165, vcc, 0, v169, vcc
	v_add_co_u32_e32 v170, vcc, 0x4af4000, v168
	global_load_dwordx4 v[160:163], v[160:161], off offset:256
	s_nop 0
	global_load_dwordx4 v[164:167], v[164:165], off offset:256
	v_addc_co_u32_e32 v171, vcc, 0, v169, vcc
	v_add_co_u32_e32 v172, vcc, 0x4b04000, v168
	s_nop 1
	v_addc_co_u32_e32 v173, vcc, 0, v169, vcc
	v_add_co_u32_e32 v180, vcc, 0x10000, v184
	global_load_dwordx4 v[168:171], v[170:171], off offset:256
	s_nop 0
	global_load_dwordx4 v[172:175], v[172:173], off offset:256
	v_addc_co_u32_e32 v181, vcc, 0, v185, vcc
	v_add_co_u32_e32 v186, vcc, 0x20000, v184
	global_load_dwordx4 v[176:179], v[184:185], off offset:256
	s_nop 0
	global_load_dwordx4 v[180:183], v[180:181], off offset:256
	v_addc_co_u32_e32 v187, vcc, 0, v185, vcc
	v_add_co_u32_e32 v188, vcc, 0x30000, v184
	s_nop 1
	v_addc_co_u32_e32 v189, vcc, 0, v185, vcc
	global_load_dwordx4 v[184:187], v[186:187], off offset:256
	s_nop 0
	global_load_dwordx4 v[188:191], v[188:189], off offset:256
.Lgi_odd_nold:
	s_cmp_ge_u32 s2, 0x780
	s_cbranch_scc1 .Lgi_odd_last
	s_waitcnt vmcnt(8)
	s_waitcnt lgkmcnt(5)
	v_mfma_f32_32x32x16_bf16 v[48:63], v[112:115], v[120:123], v[48:63]
	s_waitcnt lgkmcnt(1)
	v_mfma_f32_32x32x16_bf16 v[32:47], v[112:115], v[124:127], v[32:47]
	v_mfma_f32_32x32x16_bf16 v[16:31], v[116:119], v[120:123], v[16:31]
	v_mfma_f32_32x32x16_bf16 v[0:15], v[116:119], v[124:127], v[0:15]
	ds_write_b128 v140, v[64:67]
	ds_write_b128 v140, v[68:71] offset:4608
	ds_write_b128 v140, v[72:75] offset:9216
	ds_write_b128 v140, v[76:79] offset:13824
	ds_read_b128 v[112:115], v142 offset:36928
	ds_read_b128 v[116:119], v142 offset:41536
	ds_read_b128 v[120:123], v150 offset:64
	ds_read_b128 v[124:127], v151 offset:64
	s_waitcnt lgkmcnt(8)
	v_mfma_f32_32x32x16_bf16 v[48:63], v[96:99], v[100:103], v[48:63]
	v_mfma_f32_32x32x16_bf16 v[32:47], v[96:99], v[108:111], v[32:47]
	v_mfma_f32_32x32x16_bf16 v[16:31], v[104:107], v[100:103], v[16:31]
	v_mfma_f32_32x32x16_bf16 v[0:15], v[104:107], v[108:111], v[0:15]
	ds_write_b128 v140, v[80:83] offset:18432
	ds_write_b128 v140, v[84:87] offset:23040
	ds_write_b128 v140, v[88:91] offset:27648
	ds_write_b128 v140, v[92:95] offset:32256
	ds_read_b128 v[96:99], v142 offset:36960
	ds_read_b128 v[100:103], v142 offset:41568
	ds_read_b128 v[104:107], v150 offset:96
	ds_read_b128 v[108:111], v151 offset:96
	s_waitcnt lgkmcnt(9)
	v_mfma_f32_32x32x16_bf16 v[48:63], v[112:115], v[120:123], v[48:63]
	s_waitcnt lgkmcnt(8)
	v_mfma_f32_32x32x16_bf16 v[32:47], v[112:115], v[124:127], v[32:47]
	v_mfma_f32_32x32x16_bf16 v[16:31], v[116:119], v[120:123], v[16:31]
	v_mfma_f32_32x32x16_bf16 v[0:15], v[116:119], v[124:127], v[0:15]
	s_waitcnt lgkmcnt(1)
	v_mfma_f32_32x32x16_bf16 v[48:63], v[96:99], v[104:107], v[48:63]
	s_waitcnt lgkmcnt(0)
	v_mfma_f32_32x32x16_bf16 v[32:47], v[96:99], v[108:111], v[32:47]
	v_mfma_f32_32x32x16_bf16 v[16:31], v[100:103], v[104:107], v[16:31]
	v_mfma_f32_32x32x16_bf16 v[0:15], v[100:103], v[108:111], v[0:15]
	s_waitcnt lgkmcnt(0)
	s_barrier
	s_add_u32 s2, s2, 0x80
	s_addc_u32 s3, s3, 0
	s_branch .Lgi_even
.Lgi_odd_last:
	s_waitcnt lgkmcnt(5)
	v_mfma_f32_32x32x16_bf16 v[48:63], v[112:115], v[120:123], v[48:63]
	s_waitcnt lgkmcnt(1)
	v_mfma_f32_32x32x16_bf16 v[32:47], v[112:115], v[124:127], v[32:47]
	v_mfma_f32_32x32x16_bf16 v[16:31], v[116:119], v[120:123], v[16:31]
	v_mfma_f32_32x32x16_bf16 v[0:15], v[116:119], v[124:127], v[0:15]
	ds_read_b128 v[112:115], v142 offset:36928
	ds_read_b128 v[116:119], v142 offset:41536
	ds_read_b128 v[120:123], v150 offset:64
	ds_read_b128 v[124:127], v151 offset:64
	v_mfma_f32_32x32x16_bf16 v[48:63], v[96:99], v[100:103], v[48:63]
	s_waitcnt lgkmcnt(4)
	v_mfma_f32_32x32x16_bf16 v[32:47], v[96:99], v[108:111], v[32:47]
	v_mfma_f32_32x32x16_bf16 v[16:31], v[104:107], v[100:103], v[16:31]
	v_mfma_f32_32x32x16_bf16 v[0:15], v[104:107], v[108:111], v[0:15]
	ds_read_b128 v[96:99], v142 offset:36960
	ds_read_b128 v[100:103], v142 offset:41568
	ds_read_b128 v[104:107], v150 offset:96
	ds_read_b128 v[108:111], v151 offset:96
	s_waitcnt lgkmcnt(5)
	v_mfma_f32_32x32x16_bf16 v[48:63], v[112:115], v[120:123], v[48:63]
	s_waitcnt lgkmcnt(4)
	v_mfma_f32_32x32x16_bf16 v[32:47], v[112:115], v[124:127], v[32:47]
	v_mfma_f32_32x32x16_bf16 v[16:31], v[116:119], v[120:123], v[16:31]
	v_mfma_f32_32x32x16_bf16 v[0:15], v[116:119], v[124:127], v[0:15]
	s_waitcnt lgkmcnt(1)
	v_mfma_f32_32x32x16_bf16 v[48:63], v[96:99], v[104:107], v[48:63]
	s_waitcnt lgkmcnt(0)
	v_mfma_f32_32x32x16_bf16 v[32:47], v[96:99], v[108:111], v[32:47]
	v_mfma_f32_32x32x16_bf16 v[16:31], v[100:103], v[104:107], v[16:31]
	v_mfma_f32_32x32x16_bf16 v[0:15], v[100:103], v[108:111], v[0:15]
	s_add_u32 s2, s2, 0x80
	s_addc_u32 s3, s3, 0
	s_branch .LBB0_333

.LBB0_1591:
	ds_read_b64 v[134:135], v229 offset:63760
	ds_read_b64 v[132:133], v229 offset:63760
	ds_read_b128 v[64:67], v229 offset:63488
	ds_read_b64 v[0:1], v229 offset:63760
	ds_read_b64 v[2:3], v229 offset:63760
	v_mov_b32_e32 v14, v231
	s_ashr_i32 s39, s38, 31
	v_ashrrev_i32_e32 v8, 3, v14
	v_ashrrev_i32_e32 v9, 31, v8
	s_lshl_b64 s[4:5], s[38:39], 18
	v_lshlrev_b64 v[10:11], 11, v[8:9]
	v_lshlrev_b32_e32 v9, 4, v14
	s_waitcnt lgkmcnt(0)
	v_lshl_add_u64 v[6:7], v[2:3], 0, s[4:5]
	v_and_b32_e32 v228, 0x70, v9
	s_movk_i32 s6, 0x90
	v_lshl_add_u64 v[6:7], v[6:7], 0, v[10:11]
	v_mad_u64_u32 v[136:137], s[2:3], v8, s6, v[228:229]
	v_lshl_add_u64 v[6:7], v[6:7], 0, v[228:229]
	s_mov_b32 s2, 0x530000
	v_add_co_u32_e32 v8, vcc, s2, v6
	s_mov_b32 s2, 0x520000
	s_nop 0
	v_addc_co_u32_e32 v9, vcc, 0, v7, vcc
	v_add_co_u32_e32 v12, vcc, s2, v6
	s_ashr_i32 s41, s40, 31
	s_nop 0
	v_addc_co_u32_e32 v13, vcc, 0, v7, vcc
	s_mov_b32 s2, 0x510000
	s_lshl_b64 s[0:1], s[40:41], 18
	global_load_dwordx4 v[68:71], v[8:9], off
	global_load_dwordx4 v[72:75], v[12:13], off
	v_add_co_u32_e32 v8, vcc, s2, v6
	v_lshl_add_u64 v[4:5], v[0:1], 0, s[0:1]
	s_nop 0
	v_addc_co_u32_e32 v9, vcc, 0, v7, vcc
	s_mov_b32 s2, 0x500000
	v_lshl_add_u64 v[4:5], v[4:5], 0, v[10:11]
	v_add_co_u32_e32 v6, vcc, s2, v6
	v_lshl_add_u64 v[4:5], v[4:5], 0, v[228:229]
	s_nop 0
	v_addc_co_u32_e32 v7, vcc, 0, v7, vcc
	s_mov_b32 s2, 0x4b04000
	global_load_dwordx4 v[76:79], v[8:9], off
	global_load_dwordx4 v[80:83], v[6:7], off
	v_add_co_u32_e32 v6, vcc, s2, v4
	s_mov_b32 s2, 0x4af4000
	s_nop 0
	v_addc_co_u32_e32 v7, vcc, 0, v5, vcc
	v_add_co_u32_e32 v8, vcc, s2, v4
	s_mov_b32 s2, 0x4ae4000
	s_nop 0
	v_addc_co_u32_e32 v9, vcc, 0, v5, vcc
	global_load_dwordx4 v[84:87], v[6:7], off
	global_load_dwordx4 v[88:91], v[8:9], off
	v_add_co_u32_e32 v6, vcc, s2, v4
	s_mov_b32 s2, 0x4ad4000
	s_nop 0
	v_addc_co_u32_e32 v7, vcc, 0, v5, vcc
	v_add_co_u32_e32 v4, vcc, s2, v4
	v_ashrrev_i32_e32 v15, 1, v14
	s_nop 0
	v_addc_co_u32_e32 v5, vcc, 0, v5, vcc
	global_load_dwordx4 v[92:95], v[6:7], off
	global_load_dwordx4 v[96:99], v[4:5], off
	v_bfe_u32 v144, v14, 5, 1
	v_and_b32_e32 v137, 0xffffffc0, v15
	v_and_or_b32 v5, v14, 31, v137
	v_lshlrev_b32_e32 v4, 4, v144
	v_mad_u64_u32 v[138:139], s[2:3], v5, s6, v[4:5]
	v_and_b32_e32 v139, 0x5f, v14
	v_mad_u32_u24 v145, v139, s6, v4
	v_lshl_add_u64 v[4:5], s[4:5], 0, v[10:11]
	v_or_b32_e32 v4, v4, v228
	v_lshl_add_u64 v[140:141], v[2:3], 0, v[4:5]
	v_lshl_add_u64 v[2:3], s[0:1], 0, v[10:11]
	v_or_b32_e32 v2, v2, v228
	v_lshl_add_u64 v[142:143], v[0:1], 0, v[2:3]
	v_mov_b32_e32 v0, 0
	s_mov_b32 s2, 0
	s_mov_b64 s[0:1], 0
	v_mov_b32_e32 v1, v0
	v_mov_b32_e32 v2, v0
	v_mov_b32_e32 v3, v0
	v_mov_b32_e32 v4, v0
	v_mov_b32_e32 v5, v0
	v_mov_b32_e32 v6, v0
	v_mov_b32_e32 v7, v0
	v_mov_b32_e32 v8, v0
	v_mov_b32_e32 v9, v0
	v_mov_b32_e32 v10, v0
	v_mov_b32_e32 v11, v0
	v_mov_b32_e32 v12, v0
	v_mov_b32_e32 v13, v0
	v_mov_b32_e32 v14, v0
	v_mov_b32_e32 v15, v0
	v_mov_b32_e32 v16, v0
	v_mov_b32_e32 v17, v0
	v_mov_b32_e32 v18, v0
	v_mov_b32_e32 v19, v0
	v_mov_b32_e32 v20, v0
	v_mov_b32_e32 v21, v0
	v_mov_b32_e32 v22, v0
	v_mov_b32_e32 v23, v0
	v_mov_b32_e32 v24, v0
	v_mov_b32_e32 v25, v0
	v_mov_b32_e32 v26, v0
	v_mov_b32_e32 v27, v0
	v_mov_b32_e32 v28, v0
	v_mov_b32_e32 v29, v0
	v_mov_b32_e32 v30, v0
	v_mov_b32_e32 v31, v0
	v_mov_b32_e32 v32, v0
	v_mov_b32_e32 v33, v0
	v_mov_b32_e32 v34, v0
	v_mov_b32_e32 v35, v0
	v_mov_b32_e32 v36, v0
	v_mov_b32_e32 v37, v0
	v_mov_b32_e32 v38, v0
	v_mov_b32_e32 v39, v0
	v_mov_b32_e32 v40, v0
	v_mov_b32_e32 v41, v0
	v_mov_b32_e32 v42, v0
	v_mov_b32_e32 v43, v0
	v_mov_b32_e32 v44, v0
	v_mov_b32_e32 v45, v0
	v_mov_b32_e32 v46, v0
	v_mov_b32_e32 v47, v0
	v_mov_b32_e32 v48, v0
	v_mov_b32_e32 v49, v0
	v_mov_b32_e32 v50, v0
	v_mov_b32_e32 v51, v0
	v_mov_b32_e32 v52, v0
	v_mov_b32_e32 v53, v0
	v_mov_b32_e32 v54, v0
	v_mov_b32_e32 v55, v0
	v_mov_b32_e32 v56, v0
	v_mov_b32_e32 v57, v0
	v_mov_b32_e32 v58, v0
	v_mov_b32_e32 v59, v0
	v_mov_b32_e32 v60, v0
	v_mov_b32_e32 v61, v0
	v_mov_b32_e32 v62, v0
	v_mov_b32_e32 v63, v0
	v_lshrrev_b32_e32 v163, 3, v231
	v_cmp_gt_u32_e32 vcc, 24, v163
	v_mov_b32_e32 v164, 0xebc0
	v_mov_b32_e32 v159, 0xea00
	v_add_u32_e32 v160, 0x10fc0, v136
	v_cndmask_b32_e32 v159, v164, v159, vcc
	v_and_b32_e32 v163, 0x5f, v231
	v_cmp_gt_u32_e32 vcc, 56, v163
	v_mov_b32_e32 v164, 0xd9c0
	v_mov_b32_e32 v161, 0xd800
	v_add_u32_e32 v159, v159, v136
	v_cndmask_b32_e32 v161, v164, v161, vcc
	v_add_u32_e32 v163, 32, v163
	v_cmp_gt_u32_e32 vcc, 56, v163
	v_mov_b32_e32 v162, 0xd800
	v_add_u32_e32 v161, v161, v145
	v_add_u32_e32 v163, 0x1200, v145
	v_cndmask_b32_e32 v162, v164, v162, vcc
	v_add_u32_e32 v162, v162, v163
	v_lshl_add_u64 v[168:169], v[142:143], 0, s[0:1]
	v_add_co_u32_e32 v170, vcc, 0x4ad4000, v168
	s_nop 1
	v_addc_co_u32_e32 v171, vcc, 0, v169, vcc
	v_add_co_u32_e32 v172, vcc, 0x4ae4000, v168
	s_nop 1
	v_addc_co_u32_e32 v173, vcc, 0, v169, vcc
	global_load_dwordx4 v[196:199], v[170:171], off offset:128
	global_load_dwordx4 v[192:195], v[172:173], off offset:128
	v_add_co_u32_e32 v170, vcc, 0x4af4000, v168
	s_nop 1
	v_addc_co_u32_e32 v171, vcc, 0, v169, vcc
	v_add_co_u32_e32 v168, vcc, 0x4b04000, v168
	s_nop 1
	v_addc_co_u32_e32 v169, vcc, 0, v169, vcc
	global_load_dwordx4 v[188:191], v[170:171], off offset:128
	global_load_dwordx4 v[184:187], v[168:169], off offset:128
	v_lshl_add_u64 v[168:169], v[140:141], 0, s[0:1]
	v_add_co_u32_e32 v170, vcc, 0x500000, v168
	s_nop 1
	v_addc_co_u32_e32 v171, vcc, 0, v169, vcc
	v_add_co_u32_e32 v172, vcc, 0x510000, v168
	s_nop 1
	v_addc_co_u32_e32 v173, vcc, 0, v169, vcc
	global_load_dwordx4 v[180:183], v[170:171], off offset:128
	global_load_dwordx4 v[176:179], v[172:173], off offset:128
	v_add_co_u32_e32 v170, vcc, 0x520000, v168
	s_nop 1
	v_addc_co_u32_e32 v171, vcc, 0, v169, vcc
	v_add_co_u32_e32 v168, vcc, 0x530000, v168
	s_nop 1
	v_addc_co_u32_e32 v169, vcc, 0, v169, vcc
	global_load_dwordx4 v[172:175], v[170:171], off offset:128
	s_nop 0
	global_load_dwordx4 v[168:171], v[168:169], off offset:128
	s_waitcnt vmcnt(8)
	ds_write_b128 v136, v[96:99]
	ds_write_b128 v136, v[92:95] offset:4608
	ds_write_b128 v136, v[88:91] offset:9216
	ds_write_b128 v136, v[84:87] offset:13824
	ds_write_b128 v136, v[80:83] offset:18432
	ds_write_b128 v136, v[76:79] offset:23040
	ds_write_b128 v136, v[72:75] offset:27648
	ds_write_b128 v136, v[68:71] offset:32256
	s_waitcnt lgkmcnt(0)
	s_barrier
.Lgo2_even:
	ds_read_b128 v[116:119], v138
	ds_read_b128 v[100:103], v138 offset:32
	ds_read_b128 v[124:127], v145 offset:18432
	ds_read_b128 v[104:107], v145 offset:18464
	ds_read_b128 v[120:123], v138 offset:4608
	ds_read_b128 v[108:111], v138 offset:4640
	ds_read_b128 v[128:131], v145 offset:23040
	ds_read_b128 v[112:115], v145 offset:23072
	s_cmp_ge_u32 s0, 0x700
	s_cbranch_scc1 .Lgo2_even_nold
	v_lshl_add_u64 v[68:69], v[142:143], 0, s[0:1]
	v_add_co_u32_e32 v70, vcc, 0x4ad4000, v68
	s_nop 1
	v_addc_co_u32_e32 v71, vcc, 0, v69, vcc
	v_add_co_u32_e32 v72, vcc, 0x4ae4000, v68
	s_nop 1
	v_addc_co_u32_e32 v73, vcc, 0, v69, vcc
	global_load_dwordx4 v[96:99], v[70:71], off offset:256
	global_load_dwordx4 v[92:95], v[72:73], off offset:256
	v_add_co_u32_e32 v70, vcc, 0x4af4000, v68
	s_nop 1
	v_addc_co_u32_e32 v71, vcc, 0, v69, vcc
	v_add_co_u32_e32 v68, vcc, 0x4b04000, v68
	s_nop 1
	v_addc_co_u32_e32 v69, vcc, 0, v69, vcc
	global_load_dwordx4 v[88:91], v[70:71], off offset:256
	global_load_dwordx4 v[84:87], v[68:69], off offset:256
	v_lshl_add_u64 v[68:69], v[140:141], 0, s[0:1]
	v_add_co_u32_e32 v70, vcc, 0x500000, v68
	s_nop 1
	v_addc_co_u32_e32 v71, vcc, 0, v69, vcc
	v_add_co_u32_e32 v72, vcc, 0x510000, v68
	s_nop 1
	v_addc_co_u32_e32 v73, vcc, 0, v69, vcc
	global_load_dwordx4 v[80:83], v[70:71], off offset:256
	global_load_dwordx4 v[76:79], v[72:73], off offset:256
	v_add_co_u32_e32 v70, vcc, 0x520000, v68
	s_nop 1
	v_addc_co_u32_e32 v71, vcc, 0, v69, vcc
	v_add_co_u32_e32 v68, vcc, 0x530000, v68
	s_nop 1
	v_addc_co_u32_e32 v69, vcc, 0, v69, vcc
	global_load_dwordx4 v[72:75], v[70:71], off offset:256
	s_nop 0
	global_load_dwordx4 v[68:71], v[68:69], off offset:256
.Lgo2_even_nold:
	s_cmp_ge_u32 s0, 0x700
	s_cbranch_scc1 .Lgo2_even_w0
	s_waitcnt vmcnt(8)
	s_branch .Lgo2_even_w1

.Lgo2_even_w1:
	s_waitcnt lgkmcnt(5)
	v_mfma_f32_32x32x16_bf16 v[48:63], v[116:119], v[124:127], v[48:63]
	s_waitcnt lgkmcnt(1)
	v_mfma_f32_32x32x16_bf16 v[32:47], v[116:119], v[128:131], v[32:47]
	v_mfma_f32_32x32x16_bf16 v[16:31], v[120:123], v[124:127], v[16:31]
	v_mfma_f32_32x32x16_bf16 v[0:15], v[120:123], v[128:131], v[0:15]
	ds_write_b128 v136, v[196:199] offset:36864
	ds_write_b128 v136, v[192:195] offset:41472
	ds_write_b128 v136, v[188:191] offset:46080
	ds_write_b128 v136, v[184:187] offset:50688
	ds_read_b128 v[116:119], v138 offset:64
	ds_read_b128 v[120:123], v138 offset:4672
	ds_read_b128 v[124:127], v145 offset:18496
	ds_read_b128 v[128:131], v145 offset:23104
	s_waitcnt lgkmcnt(8)
	v_mfma_f32_32x32x16_bf16 v[48:63], v[100:103], v[104:107], v[48:63]
	v_mfma_f32_32x32x16_bf16 v[32:47], v[100:103], v[112:115], v[32:47]
	v_mfma_f32_32x32x16_bf16 v[16:31], v[108:111], v[104:107], v[16:31]
	v_mfma_f32_32x32x16_bf16 v[0:15], v[108:111], v[112:115], v[0:15]
	ds_write_b128 v136, v[180:183] offset:55296
	ds_write_b128 v159, v[176:179]
	ds_write_b128 v136, v[172:175] offset:64960
	ds_write_b128 v160, v[168:171]
	ds_read_b128 v[100:103], v138 offset:96
	ds_read_b128 v[104:107], v138 offset:4704
	ds_read_b128 v[108:111], v145 offset:18528
	ds_read_b128 v[112:115], v145 offset:23136
	s_waitcnt lgkmcnt(9)
	v_mfma_f32_32x32x16_bf16 v[48:63], v[116:119], v[124:127], v[48:63]
	s_waitcnt lgkmcnt(8)
	v_mfma_f32_32x32x16_bf16 v[32:47], v[116:119], v[128:131], v[32:47]
	v_mfma_f32_32x32x16_bf16 v[16:31], v[120:123], v[124:127], v[16:31]
	v_mfma_f32_32x32x16_bf16 v[0:15], v[120:123], v[128:131], v[0:15]
	s_waitcnt lgkmcnt(1)
	v_mfma_f32_32x32x16_bf16 v[48:63], v[100:103], v[108:111], v[48:63]
	s_waitcnt lgkmcnt(0)
	v_mfma_f32_32x32x16_bf16 v[32:47], v[100:103], v[112:115], v[32:47]
	v_mfma_f32_32x32x16_bf16 v[16:31], v[104:107], v[108:111], v[16:31]
	v_mfma_f32_32x32x16_bf16 v[0:15], v[104:107], v[112:115], v[0:15]
	s_waitcnt lgkmcnt(0)
	s_barrier
	s_add_u32 s0, s0, 0x80
	s_addc_u32 s1, s1, 0
	s_add_i32 s2, s2, 1
.Lgo2_odd:
	ds_read_b128 v[116:119], v138 offset:36864
	ds_read_b128 v[100:103], v138 offset:36896
	ds_read_b128 v[124:127], v161
	ds_read_b128 v[104:107], v161 offset:32
	ds_read_b128 v[120:123], v138 offset:41472
	ds_read_b128 v[108:111], v138 offset:41504
	ds_read_b128 v[128:131], v162
	ds_read_b128 v[112:115], v162 offset:32
	s_cmp_ge_u32 s0, 0x700
	s_cbranch_scc1 .Lgo2_odd_nold
	v_lshl_add_u64 v[168:169], v[142:143], 0, s[0:1]
	v_add_co_u32_e32 v170, vcc, 0x4ad4000, v168
	s_nop 1
	v_addc_co_u32_e32 v171, vcc, 0, v169, vcc
	v_add_co_u32_e32 v172, vcc, 0x4ae4000, v168
	s_nop 1
	v_addc_co_u32_e32 v173, vcc, 0, v169, vcc
	global_load_dwordx4 v[196:199], v[170:171], off offset:256
	global_load_dwordx4 v[192:195], v[172:173], off offset:256
	v_add_co_u32_e32 v170, vcc, 0x4af4000, v168
	s_nop 1
	v_addc_co_u32_e32 v171, vcc, 0, v169, vcc
	v_add_co_u32_e32 v168, vcc, 0x4b04000, v168
	s_nop 1
	v_addc_co_u32_e32 v169, vcc, 0, v169, vcc
	global_load_dwordx4 v[188:191], v[170:171], off offset:256
	global_load_dwordx4 v[184:187], v[168:169], off offset:256
	v_lshl_add_u64 v[168:169], v[140:141], 0, s[0:1]
	v_add_co_u32_e32 v170, vcc, 0x500000, v168
	s_nop 1
	v_addc_co_u32_e32 v171, vcc, 0, v169, vcc
	v_add_co_u32_e32 v172, vcc, 0x510000, v168
	s_nop 1
	v_addc_co_u32_e32 v173, vcc, 0, v169, vcc
	global_load_dwordx4 v[180:183], v[170:171], off offset:256
	global_load_dwordx4 v[176:179], v[172:173], off offset:256
	v_add_co_u32_e32 v170, vcc, 0x520000, v168
	s_nop 1
	v_addc_co_u32_e32 v171, vcc, 0, v169, vcc
	v_add_co_u32_e32 v168, vcc, 0x530000, v168
	s_nop 1
	v_addc_co_u32_e32 v169, vcc, 0, v169, vcc
	global_load_dwordx4 v[172:175], v[170:171], off offset:256
	s_nop 0
	global_load_dwordx4 v[168:171], v[168:169], off offset:256
.Lgo2_odd_nold:
	s_cmp_ge_u32 s0, 0x780
	s_cbranch_scc1 .Lgo2_odd_last
	s_waitcnt vmcnt(8)
	s_waitcnt lgkmcnt(5)
	v_mfma_f32_32x32x16_bf16 v[48:63], v[116:119], v[124:127], v[48:63]
	s_waitcnt lgkmcnt(1)
	v_mfma_f32_32x32x16_bf16 v[32:47], v[116:119], v[128:131], v[32:47]
	v_mfma_f32_32x32x16_bf16 v[16:31], v[120:123], v[124:127], v[16:31]
	v_mfma_f32_32x32x16_bf16 v[0:15], v[120:123], v[128:131], v[0:15]
	ds_write_b128 v136, v[96:99]
	ds_write_b128 v136, v[92:95] offset:4608
	ds_write_b128 v136, v[88:91] offset:9216
	ds_write_b128 v136, v[84:87] offset:13824
	ds_read_b128 v[116:119], v138 offset:36928
	ds_read_b128 v[120:123], v138 offset:41536
	ds_read_b128 v[124:127], v161 offset:64
	ds_read_b128 v[128:131], v162 offset:64
	s_waitcnt lgkmcnt(8)
	v_mfma_f32_32x32x16_bf16 v[48:63], v[100:103], v[104:107], v[48:63]
	v_mfma_f32_32x32x16_bf16 v[32:47], v[100:103], v[112:115], v[32:47]
	v_mfma_f32_32x32x16_bf16 v[16:31], v[108:111], v[104:107], v[16:31]
	v_mfma_f32_32x32x16_bf16 v[0:15], v[108:111], v[112:115], v[0:15]
	ds_write_b128 v136, v[80:83] offset:18432
	ds_write_b128 v136, v[76:79] offset:23040
	ds_write_b128 v136, v[72:75] offset:27648
	ds_write_b128 v136, v[68:71] offset:32256
	ds_read_b128 v[100:103], v138 offset:36960
	ds_read_b128 v[104:107], v138 offset:41568
	ds_read_b128 v[108:111], v161 offset:96
	ds_read_b128 v[112:115], v162 offset:96
	s_waitcnt lgkmcnt(9)
	v_mfma_f32_32x32x16_bf16 v[48:63], v[116:119], v[124:127], v[48:63]
	s_waitcnt lgkmcnt(8)
	v_mfma_f32_32x32x16_bf16 v[32:47], v[116:119], v[128:131], v[32:47]
	v_mfma_f32_32x32x16_bf16 v[16:31], v[120:123], v[124:127], v[16:31]
	v_mfma_f32_32x32x16_bf16 v[0:15], v[120:123], v[128:131], v[0:15]
	s_waitcnt lgkmcnt(1)
	v_mfma_f32_32x32x16_bf16 v[48:63], v[100:103], v[108:111], v[48:63]
	s_waitcnt lgkmcnt(0)
	v_mfma_f32_32x32x16_bf16 v[32:47], v[100:103], v[112:115], v[32:47]
	v_mfma_f32_32x32x16_bf16 v[16:31], v[104:107], v[108:111], v[16:31]
	v_mfma_f32_32x32x16_bf16 v[0:15], v[104:107], v[112:115], v[0:15]
	s_waitcnt lgkmcnt(0)
	s_barrier
	s_add_u32 s0, s0, 0x80
	s_addc_u32 s1, s1, 0
	s_add_i32 s2, s2, 1
	s_branch .Lgo2_even
.Lgo2_odd_last:
	s_waitcnt lgkmcnt(5)
	v_mfma_f32_32x32x16_bf16 v[48:63], v[116:119], v[124:127], v[48:63]
	s_waitcnt lgkmcnt(1)
	v_mfma_f32_32x32x16_bf16 v[32:47], v[116:119], v[128:131], v[32:47]
	v_mfma_f32_32x32x16_bf16 v[16:31], v[120:123], v[124:127], v[16:31]
	v_mfma_f32_32x32x16_bf16 v[0:15], v[120:123], v[128:131], v[0:15]
	ds_read_b128 v[116:119], v138 offset:36928
	ds_read_b128 v[120:123], v138 offset:41536
	ds_read_b128 v[124:127], v161 offset:64
	ds_read_b128 v[128:131], v162 offset:64
	v_mfma_f32_32x32x16_bf16 v[48:63], v[100:103], v[104:107], v[48:63]
	s_waitcnt lgkmcnt(4)
	v_mfma_f32_32x32x16_bf16 v[32:47], v[100:103], v[112:115], v[32:47]
	v_mfma_f32_32x32x16_bf16 v[16:31], v[108:111], v[104:107], v[16:31]
	v_mfma_f32_32x32x16_bf16 v[0:15], v[108:111], v[112:115], v[0:15]
	ds_read_b128 v[100:103], v138 offset:36960
	ds_read_b128 v[104:107], v138 offset:41568
	ds_read_b128 v[108:111], v161 offset:96
	ds_read_b128 v[112:115], v162 offset:96
	s_waitcnt lgkmcnt(5)
	v_mfma_f32_32x32x16_bf16 v[48:63], v[116:119], v[124:127], v[48:63]
	s_waitcnt lgkmcnt(4)
	v_mfma_f32_32x32x16_bf16 v[32:47], v[116:119], v[128:131], v[32:47]
	v_mfma_f32_32x32x16_bf16 v[16:31], v[120:123], v[124:127], v[16:31]
	v_mfma_f32_32x32x16_bf16 v[0:15], v[120:123], v[128:131], v[0:15]
	s_waitcnt lgkmcnt(1)
	v_mfma_f32_32x32x16_bf16 v[48:63], v[100:103], v[108:111], v[48:63]
	s_waitcnt lgkmcnt(0)
	v_mfma_f32_32x32x16_bf16 v[32:47], v[100:103], v[112:115], v[32:47]
	v_mfma_f32_32x32x16_bf16 v[16:31], v[104:107], v[108:111], v[16:31]
	v_mfma_f32_32x32x16_bf16 v[0:15], v[104:107], v[112:115], v[0:15]
	s_add_u32 s0, s0, 0x80
	s_addc_u32 s1, s1, 0
	s_add_i32 s2, s2, 1
	s_branch .LBB0_1595

	.amdhsa_kernel _Z11mega_kernel6Params
		.amdhsa_group_segment_fixed_size 74240
		.amdhsa_private_segment_fixed_size 0
		.amdhsa_kernarg_size 536
		.amdhsa_user_sgpr_count 2
		.amdhsa_user_sgpr_dispatch_ptr 0
		.amdhsa_user_sgpr_queue_ptr 0
		.amdhsa_user_sgpr_kernarg_segment_ptr 1
		.amdhsa_user_sgpr_dispatch_id 0
		.amdhsa_user_sgpr_kernarg_preload_length 0
		.amdhsa_user_sgpr_kernarg_preload_offset 0
		.amdhsa_user_sgpr_private_segment_size 0
		.amdhsa_uses_dynamic_stack 0
		.amdhsa_enable_private_segment 0
		.amdhsa_system_sgpr_workgroup_id_x 1
		.amdhsa_system_sgpr_workgroup_id_y 0
		.amdhsa_system_sgpr_workgroup_id_z 0
		.amdhsa_system_sgpr_workgroup_info 0
		.amdhsa_system_vgpr_workitem_id 2
		.amdhsa_next_free_vgpr 256
		.amdhsa_next_free_sgpr 100
		.amdhsa_accum_offset 256
		.amdhsa_reserve_vcc 1
		.amdhsa_float_round_mode_32 0
		.amdhsa_float_round_mode_16_64 0
		.amdhsa_float_denorm_mode_32 3
		.amdhsa_float_denorm_mode_16_64 3
		.amdhsa_dx10_clamp 1
		.amdhsa_ieee_mode 1
		.amdhsa_fp16_overflow 0
		.amdhsa_tg_split 0
		.amdhsa_exception_fp_ieee_invalid_op 0
		.amdhsa_exception_fp_denorm_src 0
		.amdhsa_exception_fp_ieee_div_zero 0
		.amdhsa_exception_fp_ieee_overflow 0
		.amdhsa_exception_fp_ieee_underflow 0
		.amdhsa_exception_fp_ieee_inexact 0
		.amdhsa_exception_int_div_zero 0
	.end_amdhsa_kernel

amdhsa.kernels:
  - .agpr_count:     0
    .args:
      - .offset:         0
        .size:           280
        .value_kind:     by_value
      - .offset:         280
        .size:           4
        .value_kind:     hidden_block_count_x
      - .offset:         284
        .size:           4
        .value_kind:     hidden_block_count_y
      - .offset:         288
        .size:           4
        .value_kind:     hidden_block_count_z
      - .offset:         292
        .size:           2
        .value_kind:     hidden_group_size_x
      - .offset:         294
        .size:           2
        .value_kind:     hidden_group_size_y
      - .offset:         296
        .size:           2
        .value_kind:     hidden_group_size_z
      - .offset:         298
        .size:           2
        .value_kind:     hidden_remainder_x
      - .offset:         300
        .size:           2
        .value_kind:     hidden_remainder_y
      - .offset:         302
        .size:           2
        .value_kind:     hidden_remainder_z
      - .offset:         320
        .size:           8
        .value_kind:     hidden_global_offset_x
      - .offset:         328
        .size:           8
        .value_kind:     hidden_global_offset_y
      - .offset:         336
        .size:           8
        .value_kind:     hidden_global_offset_z
      - .offset:         344
        .size:           2
        .value_kind:     hidden_grid_dims
      - .offset:         368
        .size:           8
        .value_kind:     hidden_multigrid_sync_arg
    .group_segment_fixed_size: 74240
    .kernarg_segment_align: 8
    .kernarg_segment_size: 536
    .language:       OpenCL C
    .language_version:
      - 2
      - 0
    .max_flat_workgroup_size: 256
    .name:           _Z11mega_kernel6Params
    .private_segment_fixed_size: 0
    .sgpr_count:     106
    .sgpr_spill_count: 82
    .symbol:         _Z11mega_kernel6Params.kd
    .uniform_work_group_size: 1
    .uses_dynamic_stack: false
    .vgpr_count:     256
    .vgpr_spill_count: 0
    .wavefront_size: 64
